# v86 + out-proj epilogue: residual loads of row blocks 1-7 prefetched three blocks ahead into dead K-loop registers; per-pair waits dropped
# speedup vs baseline: 1.0107x; 1.0107x over previous
.LBB0_1279:
	s_lshl_b32 s15, s54, 8
	s_add_i32 s15, s15, s79
	v_mbcnt_lo_u32_b32 v156, -1, 0
	v_mbcnt_hi_u32_b32 v156, -1, v156
	v_readlane_b32 s17, v252, 33
	v_and_or_b32 v140, v156, 15, s15
	s_lshl_b32 s15, s53, 8
	v_ashrrev_i32_e32 v141, 1, v156
	s_or_b32 s15, s15, s17
	v_and_b32_e32 v141, -8, v141
	v_add_u32_e32 v146, s15, v141
	v_ashrrev_i32_e32 v141, 31, v140
	v_ashrrev_i32_e32 v147, 31, v146
	v_lshlrev_b64 v[142:143], 11, v[140:141]
	v_lshl_add_u64 v[144:145], v[142:143], 0, v[146:147]
	v_lshlrev_b64 v[142:143], 2, v[144:145]
	v_lshl_add_u64 v[150:151], s[0:1], 0, v[142:143]
	global_load_dwordx4 v[158:161], v[150:151], off offset:16 nt
	global_load_dwordx4 v[162:165], v[150:151], off nt
	v_mov_b32_e32 v226, v150
	v_mov_b32_e32 v227, v151
	v_mov_b32_e32 v246, 0x20000
	v_mov_b32_e32 v247, 0
	v_lshl_add_u64 v[228:229], v[226:227], 0, v[246:247]
	global_load_dwordx4 v[168:171], v[228:229], off nt
	global_load_dwordx4 v[172:175], v[228:229], off offset:16 nt
	global_load_dwordx4 v[176:179], v[228:229], off offset:512 nt
	global_load_dwordx4 v[180:183], v[228:229], off offset:528 nt
	v_mov_b32_e32 v246, 0x40000
	v_mov_b32_e32 v247, 0
	v_lshl_add_u64 v[228:229], v[226:227], 0, v[246:247]
	global_load_dwordx4 v[184:187], v[228:229], off nt
	global_load_dwordx4 v[188:191], v[228:229], off offset:16 nt
	global_load_dwordx4 v[192:195], v[228:229], off offset:512 nt
	global_load_dwordx4 v[206:209], v[228:229], off offset:528 nt
	v_mov_b32_e32 v246, 0x60000
	v_mov_b32_e32 v247, 0
	v_lshl_add_u64 v[228:229], v[226:227], 0, v[246:247]
	global_load_dwordx4 v[210:213], v[228:229], off nt
	global_load_dwordx4 v[214:217], v[228:229], off offset:16 nt
	global_load_dwordx4 v[218:221], v[228:229], off offset:512 nt
	global_load_dwordx4 v[222:225], v[228:229], off offset:528 nt
	v_lshl_add_u64 v[152:153], s[10:11], 0, v[142:143]
	v_cndmask_b32_e64 v142, 0, 1, s[12:13]
	v_cmp_ne_u32_e64 s[92:93], 1, v142
	s_andn2_b64 vcc, exec, s[12:13]
	v_lshl_add_u64 v[142:143], v[146:147], 2, s[4:5]
	v_lshl_add_u64 v[148:149], v[144:145], 1, s[6:7]
	s_waitcnt vmcnt(0)
	v_pk_add_f32 v[124:125], v[124:125], v[160:161]
	v_pk_add_f32 v[128:129], v[128:129], v[164:165]
	v_pk_add_f32 v[126:127], v[126:127], v[162:163]
	v_pk_add_f32 v[122:123], v[122:123], v[158:159]
	global_store_dwordx4 v[152:153], v[126:129], off
	global_store_dwordx4 v[152:153], v[122:125], off offset:16
	s_cbranch_vccnz .LBB0_1281
	global_load_dwordx4 v[234:237], v[142:143], off offset:16
	global_load_dwordx4 v[230:233], v[142:143], off
	global_load_dwordx4 v[242:245], v[142:143], off offset:528
	global_load_dwordx4 v[238:241], v[142:143], off offset:512
	s_waitcnt vmcnt(0)
	v_mov_b32_e32 v158, v234
	v_mov_b32_e32 v159, v235
	v_mov_b32_e32 v160, v236
	v_mov_b32_e32 v161, v237
	v_mov_b32_e32 v162, v230
	v_mov_b32_e32 v163, v231
	v_mov_b32_e32 v164, v232
	v_mov_b32_e32 v165, v233
	v_pk_mul_f32 v[166:167], v[124:125], v[160:161]
	v_pk_mul_f32 v[162:163], v[126:127], v[162:163]
	v_pk_mul_f32 v[126:127], v[126:127], v[126:127]
	v_pk_mul_f32 v[164:165], v[128:129], v[164:165]
	v_pk_mul_f32 v[128:129], v[128:129], v[128:129]
	v_add_f32_e32 v126, v126, v127
	v_add_f32_e32 v126, v128, v126
	v_pk_mul_f32 v[160:161], v[122:123], v[158:159]
	v_pk_mul_f32 v[122:123], v[122:123], v[122:123]
	v_add_f32_e32 v126, v129, v126
	v_add_f32_e32 v122, v122, v126
	v_pk_mul_f32 v[124:125], v[124:125], v[124:125]
	v_add_f32_e32 v122, v123, v122
	v_add_f32_e32 v122, v124, v122
	v_add_f32_e32 v122, v125, v122
	v_cvt_pk_bf16_f32 v158, v162, v163
	v_cvt_pk_bf16_f32 v159, v164, v165
	v_cvt_pk_bf16_f32 v160, v160, v161
	v_cvt_pk_bf16_f32 v161, v166, v167
	global_store_dwordx4 v[148:149], v[158:161], off
	s_branch .LBB0_1282

.LBB0_1286:
	s_nop 0
	v_or_b32_e32 v114, 16, v140
	s_waitcnt lgkmcnt(0)
	v_ashrrev_i32_e32 v115, 31, v114
	v_lshlrev_b64 v[114:115], 11, v[114:115]
	v_lshl_add_u64 v[114:115], v[114:115], 0, v[146:147]
	v_lshlrev_b64 v[116:117], 2, v[114:115]
	v_lshl_add_u64 v[118:119], s[0:1], 0, v[116:117]
	s_waitcnt vmcnt(16)
	v_mov_b32_e32 v120, v168
	v_mov_b32_e32 v121, v169
	v_mov_b32_e32 v122, v170
	v_mov_b32_e32 v123, v171
	v_mov_b32_e32 v124, v172
	v_mov_b32_e32 v125, v173
	v_mov_b32_e32 v126, v174
	v_mov_b32_e32 v127, v175
	s_and_b64 vcc, exec, s[92:93]
	v_lshl_add_u64 v[116:117], s[10:11], 0, v[116:117]
	v_lshl_add_u64 v[114:115], v[114:115], 1, s[6:7]
	v_pk_add_f32 v[112:113], v[112:113], v[122:123]
	v_pk_add_f32 v[110:111], v[110:111], v[120:121]
	v_pk_add_f32 v[108:109], v[108:109], v[126:127]
	v_pk_add_f32 v[106:107], v[106:107], v[124:125]
	global_store_dwordx4 v[116:117], v[110:113], off
	global_store_dwordx4 v[116:117], v[106:109], off offset:16
	s_cbranch_vccnz .LBB0_1288
	v_mov_b32_e32 v120, v234
	v_mov_b32_e32 v121, v235
	v_mov_b32_e32 v122, v236
	v_mov_b32_e32 v123, v237
	v_mov_b32_e32 v124, v230
	v_mov_b32_e32 v125, v231
	v_mov_b32_e32 v126, v232
	v_mov_b32_e32 v127, v233
	v_pk_mul_f32 v[128:129], v[108:109], v[122:123]
	v_pk_mul_f32 v[124:125], v[110:111], v[124:125]
	v_pk_mul_f32 v[110:111], v[110:111], v[110:111]
	v_pk_mul_f32 v[126:127], v[112:113], v[126:127]
	v_pk_mul_f32 v[112:113], v[112:113], v[112:113]
	v_add_f32_e32 v110, v110, v111
	v_add_f32_e32 v110, v112, v110
	v_pk_mul_f32 v[122:123], v[106:107], v[120:121]
	v_pk_mul_f32 v[106:107], v[106:107], v[106:107]
	v_add_f32_e32 v110, v113, v110
	v_add_f32_e32 v106, v106, v110
	v_pk_mul_f32 v[108:109], v[108:109], v[108:109]
	v_add_f32_e32 v106, v107, v106
	v_add_f32_e32 v106, v108, v106
	v_add_f32_e32 v106, v109, v106
	v_cvt_pk_bf16_f32 v120, v124, v125
	v_cvt_pk_bf16_f32 v121, v126, v127
	v_cvt_pk_bf16_f32 v122, v122, v123
	v_cvt_pk_bf16_f32 v123, v128, v129
	global_store_dwordx4 v[114:115], v[120:123], off
	s_branch .LBB0_1289

.LBB0_1289:
	v_mov_b32_e32 v108, v176
	v_mov_b32_e32 v109, v177
	v_mov_b32_e32 v110, v178
	v_mov_b32_e32 v111, v179
	s_nop 0
	v_mov_b32_e32 v118, v180
	v_mov_b32_e32 v119, v181
	v_mov_b32_e32 v120, v182
	v_mov_b32_e32 v121, v183
	v_mov_b32_e32 v246, 0x100000
	v_mov_b32_e32 v247, 0
	v_lshl_add_u64 v[228:229], v[226:227], 0, v[246:247]
	global_load_dwordx4 v[168:171], v[228:229], off nt
	global_load_dwordx4 v[172:175], v[228:229], off offset:16 nt
	global_load_dwordx4 v[176:179], v[228:229], off offset:512 nt
	global_load_dwordx4 v[180:183], v[228:229], off offset:528 nt
	s_and_b64 vcc, exec, s[92:93]
	v_pk_add_f32 v[104:105], v[104:105], v[110:111]
	v_pk_add_f32 v[102:103], v[102:103], v[108:109]
	v_pk_add_f32 v[100:101], v[100:101], v[120:121]
	v_pk_add_f32 v[98:99], v[98:99], v[118:119]
	global_store_dwordx4 v[116:117], v[102:105], off offset:512
	global_store_dwordx4 v[116:117], v[98:101], off offset:528
	s_cbranch_vccnz .LBB0_1293
	v_mov_b32_e32 v108, v242
	v_mov_b32_e32 v109, v243
	v_mov_b32_e32 v110, v244
	v_mov_b32_e32 v111, v245
	v_mov_b32_e32 v116, v238
	v_mov_b32_e32 v117, v239
	v_mov_b32_e32 v118, v240
	v_mov_b32_e32 v119, v241
	v_pk_mul_f32 v[116:117], v[102:103], v[116:117]
	v_mul_f32_e32 v103, v103, v103
	v_fmac_f32_e32 v103, v102, v102
	v_fmac_f32_e32 v103, v104, v104
	v_fmac_f32_e32 v103, v105, v105
	v_fmac_f32_e32 v103, v98, v98
	v_fmac_f32_e32 v103, v99, v99
	v_pk_mul_f32 v[112:113], v[104:105], v[118:119]
	v_pk_mul_f32 v[118:119], v[100:101], v[110:111]
	v_fmac_f32_e32 v103, v100, v100
	v_and_b32_e32 v100, 64, v200
	v_pk_mul_f32 v[110:111], v[98:99], v[108:109]
	v_xor_b32_e32 v99, 16, v200
	v_add_u32_e32 v100, 64, v100
	v_cmp_lt_i32_e32 vcc, v99, v100
	v_fmac_f32_e32 v103, v101, v101
	v_add_f32_e32 v98, v106, v103
	v_cndmask_b32_e32 v99, v200, v99, vcc
	v_lshlrev_b32_e32 v99, 2, v99
	ds_bpermute_b32 v99, v99, v98
	v_cvt_pk_bf16_f32 v108, v116, v117
	v_cvt_pk_bf16_f32 v109, v112, v113
	v_cvt_pk_bf16_f32 v110, v110, v111
	v_cvt_pk_bf16_f32 v111, v118, v119
	s_waitcnt lgkmcnt(0)
	v_add_f32_e32 v98, v98, v99
	v_xor_b32_e32 v99, 32, v200
	v_cmp_lt_i32_e32 vcc, v99, v100
	global_store_dwordx4 v[114:115], v[108:111], off offset:256
	s_nop 0
	v_cndmask_b32_e32 v99, v200, v99, vcc
	v_lshlrev_b32_e32 v99, 2, v99
	ds_bpermute_b32 v99, v99, v98
	s_and_saveexec_b64 s[22:23], s[90:91]
	s_cbranch_execz .LBB0_1292
	v_lshl_add_u64 v[100:101], v[140:141], 2, s[8:9]
	s_waitcnt lgkmcnt(0)
	v_add_f32_e32 v98, v98, v99
	global_atomic_add_f32 v[100:101], v98, off offset:64

.LBB0_1293:
	s_nop 0
	v_or_b32_e32 v98, 32, v140
	s_waitcnt lgkmcnt(0)
	v_ashrrev_i32_e32 v99, 31, v98
	v_lshlrev_b64 v[98:99], 11, v[98:99]
	v_lshl_add_u64 v[98:99], v[98:99], 0, v[146:147]
	v_lshlrev_b64 v[100:101], 2, v[98:99]
	v_lshl_add_u64 v[102:103], s[0:1], 0, v[100:101]
	s_waitcnt vmcnt(16)
	v_mov_b32_e32 v104, v184
	v_mov_b32_e32 v105, v185
	v_mov_b32_e32 v106, v186
	v_mov_b32_e32 v107, v187
	v_mov_b32_e32 v108, v188
	v_mov_b32_e32 v109, v189
	v_mov_b32_e32 v110, v190
	v_mov_b32_e32 v111, v191
	s_and_b64 vcc, exec, s[92:93]
	v_lshl_add_u64 v[100:101], s[10:11], 0, v[100:101]
	v_lshl_add_u64 v[98:99], v[98:99], 1, s[6:7]
	v_pk_add_f32 v[96:97], v[96:97], v[106:107]
	v_pk_add_f32 v[94:95], v[94:95], v[104:105]
	v_pk_add_f32 v[92:93], v[92:93], v[110:111]
	v_pk_add_f32 v[90:91], v[90:91], v[108:109]
	global_store_dwordx4 v[100:101], v[94:97], off
	global_store_dwordx4 v[100:101], v[90:93], off offset:16
	s_cbranch_vccnz .LBB0_1295
	v_mov_b32_e32 v104, v234
	v_mov_b32_e32 v105, v235
	v_mov_b32_e32 v106, v236
	v_mov_b32_e32 v107, v237
	v_mov_b32_e32 v108, v230
	v_mov_b32_e32 v109, v231
	v_mov_b32_e32 v110, v232
	v_mov_b32_e32 v111, v233
	v_pk_mul_f32 v[112:113], v[92:93], v[106:107]
	v_pk_mul_f32 v[108:109], v[94:95], v[108:109]
	v_pk_mul_f32 v[94:95], v[94:95], v[94:95]
	v_pk_mul_f32 v[110:111], v[96:97], v[110:111]
	v_pk_mul_f32 v[96:97], v[96:97], v[96:97]
	v_add_f32_e32 v94, v94, v95
	v_add_f32_e32 v94, v96, v94
	v_pk_mul_f32 v[106:107], v[90:91], v[104:105]
	v_pk_mul_f32 v[90:91], v[90:91], v[90:91]
	v_add_f32_e32 v94, v97, v94
	v_add_f32_e32 v90, v90, v94
	v_pk_mul_f32 v[92:93], v[92:93], v[92:93]
	v_add_f32_e32 v90, v91, v90
	v_add_f32_e32 v90, v92, v90
	v_add_f32_e32 v90, v93, v90
	v_cvt_pk_bf16_f32 v104, v108, v109
	v_cvt_pk_bf16_f32 v105, v110, v111
	v_cvt_pk_bf16_f32 v106, v106, v107
	v_cvt_pk_bf16_f32 v107, v112, v113
	global_store_dwordx4 v[98:99], v[104:107], off
	s_branch .LBB0_1296

.LBB0_1296:
	v_mov_b32_e32 v92, v192
	v_mov_b32_e32 v93, v193
	v_mov_b32_e32 v94, v194
	v_mov_b32_e32 v95, v195
	s_nop 0
	v_mov_b32_e32 v102, v206
	v_mov_b32_e32 v103, v207
	v_mov_b32_e32 v104, v208
	v_mov_b32_e32 v105, v209
	v_mov_b32_e32 v246, 0x120000
	v_mov_b32_e32 v247, 0
	v_lshl_add_u64 v[228:229], v[226:227], 0, v[246:247]
	global_load_dwordx4 v[184:187], v[228:229], off nt
	global_load_dwordx4 v[188:191], v[228:229], off offset:16 nt
	global_load_dwordx4 v[192:195], v[228:229], off offset:512 nt
	global_load_dwordx4 v[206:209], v[228:229], off offset:528 nt
	s_and_b64 vcc, exec, s[92:93]
	v_pk_add_f32 v[88:89], v[88:89], v[94:95]
	v_pk_add_f32 v[86:87], v[86:87], v[92:93]
	v_pk_add_f32 v[84:85], v[84:85], v[104:105]
	v_pk_add_f32 v[82:83], v[82:83], v[102:103]
	global_store_dwordx4 v[100:101], v[86:89], off offset:512
	global_store_dwordx4 v[100:101], v[82:85], off offset:528
	s_cbranch_vccnz .LBB0_1300
	v_mov_b32_e32 v92, v242
	v_mov_b32_e32 v93, v243
	v_mov_b32_e32 v94, v244
	v_mov_b32_e32 v95, v245
	v_mov_b32_e32 v100, v238
	v_mov_b32_e32 v101, v239
	v_mov_b32_e32 v102, v240
	v_mov_b32_e32 v103, v241
	v_pk_mul_f32 v[100:101], v[86:87], v[100:101]
	v_mul_f32_e32 v87, v87, v87
	v_fmac_f32_e32 v87, v86, v86
	v_fmac_f32_e32 v87, v88, v88
	v_fmac_f32_e32 v87, v89, v89
	v_fmac_f32_e32 v87, v82, v82
	v_fmac_f32_e32 v87, v83, v83
	v_pk_mul_f32 v[96:97], v[88:89], v[102:103]
	v_pk_mul_f32 v[102:103], v[84:85], v[94:95]
	v_fmac_f32_e32 v87, v84, v84
	v_and_b32_e32 v84, 64, v200
	v_pk_mul_f32 v[94:95], v[82:83], v[92:93]
	v_xor_b32_e32 v83, 16, v200
	v_add_u32_e32 v84, 64, v84
	v_cmp_lt_i32_e32 vcc, v83, v84
	v_fmac_f32_e32 v87, v85, v85
	v_add_f32_e32 v82, v90, v87
	v_cndmask_b32_e32 v83, v200, v83, vcc
	v_lshlrev_b32_e32 v83, 2, v83
	ds_bpermute_b32 v83, v83, v82
	v_cvt_pk_bf16_f32 v92, v100, v101
	v_cvt_pk_bf16_f32 v93, v96, v97
	v_cvt_pk_bf16_f32 v94, v94, v95
	v_cvt_pk_bf16_f32 v95, v102, v103
	s_waitcnt lgkmcnt(0)
	v_add_f32_e32 v82, v82, v83
	v_xor_b32_e32 v83, 32, v200
	v_cmp_lt_i32_e32 vcc, v83, v84
	global_store_dwordx4 v[98:99], v[92:95], off offset:256
	s_nop 0
	v_cndmask_b32_e32 v83, v200, v83, vcc
	v_lshlrev_b32_e32 v83, 2, v83
	ds_bpermute_b32 v83, v83, v82
	s_and_saveexec_b64 s[22:23], s[90:91]
	s_cbranch_execz .LBB0_1299
	v_lshl_add_u64 v[84:85], v[140:141], 2, s[8:9]
	s_waitcnt lgkmcnt(0)
	v_add_f32_e32 v82, v82, v83
	global_atomic_add_f32 v[84:85], v82, off offset:128

.LBB0_1300:
	s_nop 0
	v_or_b32_e32 v82, 48, v140
	s_waitcnt lgkmcnt(0)
	v_ashrrev_i32_e32 v83, 31, v82
	v_lshlrev_b64 v[82:83], 11, v[82:83]
	v_lshl_add_u64 v[82:83], v[82:83], 0, v[146:147]
	v_lshlrev_b64 v[84:85], 2, v[82:83]
	v_lshl_add_u64 v[86:87], s[0:1], 0, v[84:85]
	s_waitcnt vmcnt(16)
	v_mov_b32_e32 v88, v210
	v_mov_b32_e32 v89, v211
	v_mov_b32_e32 v90, v212
	v_mov_b32_e32 v91, v213
	v_mov_b32_e32 v92, v214
	v_mov_b32_e32 v93, v215
	v_mov_b32_e32 v94, v216
	v_mov_b32_e32 v95, v217
	s_and_b64 vcc, exec, s[92:93]
	v_lshl_add_u64 v[84:85], s[10:11], 0, v[84:85]
	v_lshl_add_u64 v[82:83], v[82:83], 1, s[6:7]
	v_pk_add_f32 v[80:81], v[80:81], v[90:91]
	v_pk_add_f32 v[78:79], v[78:79], v[88:89]
	v_pk_add_f32 v[76:77], v[76:77], v[94:95]
	v_pk_add_f32 v[74:75], v[74:75], v[92:93]
	global_store_dwordx4 v[84:85], v[78:81], off
	global_store_dwordx4 v[84:85], v[74:77], off offset:16
	s_cbranch_vccnz .LBB0_1302
	v_mov_b32_e32 v88, v234
	v_mov_b32_e32 v89, v235
	v_mov_b32_e32 v90, v236
	v_mov_b32_e32 v91, v237
	v_mov_b32_e32 v92, v230
	v_mov_b32_e32 v93, v231
	v_mov_b32_e32 v94, v232
	v_mov_b32_e32 v95, v233
	v_pk_mul_f32 v[96:97], v[76:77], v[90:91]
	v_pk_mul_f32 v[92:93], v[78:79], v[92:93]
	v_pk_mul_f32 v[78:79], v[78:79], v[78:79]
	v_pk_mul_f32 v[94:95], v[80:81], v[94:95]
	v_pk_mul_f32 v[80:81], v[80:81], v[80:81]
	v_add_f32_e32 v78, v78, v79
	v_add_f32_e32 v78, v80, v78
	v_pk_mul_f32 v[90:91], v[74:75], v[88:89]
	v_pk_mul_f32 v[74:75], v[74:75], v[74:75]
	v_add_f32_e32 v78, v81, v78
	v_add_f32_e32 v74, v74, v78
	v_pk_mul_f32 v[76:77], v[76:77], v[76:77]
	v_add_f32_e32 v74, v75, v74
	v_add_f32_e32 v74, v76, v74
	v_add_f32_e32 v74, v77, v74
	v_cvt_pk_bf16_f32 v88, v92, v93
	v_cvt_pk_bf16_f32 v89, v94, v95
	v_cvt_pk_bf16_f32 v90, v90, v91
	v_cvt_pk_bf16_f32 v91, v96, v97
	global_store_dwordx4 v[82:83], v[88:91], off
	s_branch .LBB0_1303

.LBB0_1303:
	v_mov_b32_e32 v76, v218
	v_mov_b32_e32 v77, v219
	v_mov_b32_e32 v78, v220
	v_mov_b32_e32 v79, v221
	s_nop 0
	v_mov_b32_e32 v86, v222
	v_mov_b32_e32 v87, v223
	v_mov_b32_e32 v88, v224
	v_mov_b32_e32 v89, v225
	v_mov_b32_e32 v246, 0x140000
	v_mov_b32_e32 v247, 0
	v_lshl_add_u64 v[228:229], v[226:227], 0, v[246:247]
	global_load_dwordx4 v[210:213], v[228:229], off nt
	global_load_dwordx4 v[214:217], v[228:229], off offset:16 nt
	global_load_dwordx4 v[218:221], v[228:229], off offset:512 nt
	global_load_dwordx4 v[222:225], v[228:229], off offset:528 nt
	s_and_b64 vcc, exec, s[92:93]
	v_pk_add_f32 v[72:73], v[72:73], v[78:79]
	v_pk_add_f32 v[70:71], v[70:71], v[76:77]
	v_pk_add_f32 v[68:69], v[68:69], v[88:89]
	v_pk_add_f32 v[66:67], v[66:67], v[86:87]
	global_store_dwordx4 v[84:85], v[70:73], off offset:512
	global_store_dwordx4 v[84:85], v[66:69], off offset:528
	s_cbranch_vccnz .LBB0_1307
	v_mov_b32_e32 v76, v242
	v_mov_b32_e32 v77, v243
	v_mov_b32_e32 v78, v244
	v_mov_b32_e32 v79, v245
	v_mov_b32_e32 v84, v238
	v_mov_b32_e32 v85, v239
	v_mov_b32_e32 v86, v240
	v_mov_b32_e32 v87, v241
	v_pk_mul_f32 v[84:85], v[70:71], v[84:85]
	v_mul_f32_e32 v71, v71, v71
	v_fmac_f32_e32 v71, v70, v70
	v_fmac_f32_e32 v71, v72, v72
	v_fmac_f32_e32 v71, v73, v73
	v_fmac_f32_e32 v71, v66, v66
	v_fmac_f32_e32 v71, v67, v67
	v_pk_mul_f32 v[80:81], v[72:73], v[86:87]
	v_pk_mul_f32 v[86:87], v[68:69], v[78:79]
	v_fmac_f32_e32 v71, v68, v68
	v_and_b32_e32 v68, 64, v200
	v_pk_mul_f32 v[78:79], v[66:67], v[76:77]
	v_xor_b32_e32 v67, 16, v200
	v_add_u32_e32 v68, 64, v68
	v_cmp_lt_i32_e32 vcc, v67, v68
	v_fmac_f32_e32 v71, v69, v69
	v_add_f32_e32 v66, v74, v71
	v_cndmask_b32_e32 v67, v200, v67, vcc
	v_lshlrev_b32_e32 v67, 2, v67
	ds_bpermute_b32 v67, v67, v66
	v_cvt_pk_bf16_f32 v76, v84, v85
	v_cvt_pk_bf16_f32 v77, v80, v81
	v_cvt_pk_bf16_f32 v78, v78, v79
	v_cvt_pk_bf16_f32 v79, v86, v87
	s_waitcnt lgkmcnt(0)
	v_add_f32_e32 v66, v66, v67
	v_xor_b32_e32 v67, 32, v200
	v_cmp_lt_i32_e32 vcc, v67, v68
	global_store_dwordx4 v[82:83], v[76:79], off offset:256
	s_nop 0
	v_cndmask_b32_e32 v67, v200, v67, vcc
	v_lshlrev_b32_e32 v67, 2, v67
	ds_bpermute_b32 v67, v67, v66
	s_and_saveexec_b64 s[22:23], s[90:91]
	s_cbranch_execz .LBB0_1306
	v_lshl_add_u64 v[68:69], v[140:141], 2, s[8:9]
	s_waitcnt lgkmcnt(0)
	v_add_f32_e32 v66, v66, v67
	global_atomic_add_f32 v[68:69], v66, off offset:192

.LBB0_1307:
	s_mov_b64 s[22:23], 0x40000
	s_waitcnt lgkmcnt(0)
	v_lshl_add_u64 v[66:67], v[144:145], 0, s[22:23]
	v_lshlrev_b64 v[68:69], 2, v[66:67]
	v_lshl_add_u64 v[70:71], s[0:1], 0, v[68:69]
	s_waitcnt vmcnt(16)
	v_mov_b32_e32 v72, v168
	v_mov_b32_e32 v73, v169
	v_mov_b32_e32 v74, v170
	v_mov_b32_e32 v75, v171
	v_mov_b32_e32 v76, v172
	v_mov_b32_e32 v77, v173
	v_mov_b32_e32 v78, v174
	v_mov_b32_e32 v79, v175
	s_and_b64 vcc, exec, s[92:93]
	v_lshl_add_u64 v[68:69], s[10:11], 0, v[68:69]
	v_lshl_add_u64 v[66:67], v[66:67], 1, s[6:7]
	v_pk_add_f32 v[64:65], v[64:65], v[74:75]
	v_pk_add_f32 v[62:63], v[62:63], v[72:73]
	v_pk_add_f32 v[60:61], v[60:61], v[78:79]
	v_pk_add_f32 v[58:59], v[58:59], v[76:77]
	global_store_dwordx4 v[68:69], v[62:65], off
	global_store_dwordx4 v[68:69], v[58:61], off offset:16
	s_cbranch_vccnz .LBB0_1309
	v_mov_b32_e32 v72, v234
	v_mov_b32_e32 v73, v235
	v_mov_b32_e32 v74, v236
	v_mov_b32_e32 v75, v237
	v_mov_b32_e32 v76, v230
	v_mov_b32_e32 v77, v231
	v_mov_b32_e32 v78, v232
	v_mov_b32_e32 v79, v233
	v_pk_mul_f32 v[80:81], v[60:61], v[74:75]
	v_pk_mul_f32 v[76:77], v[62:63], v[76:77]
	v_pk_mul_f32 v[62:63], v[62:63], v[62:63]
	v_pk_mul_f32 v[78:79], v[64:65], v[78:79]
	v_pk_mul_f32 v[64:65], v[64:65], v[64:65]
	v_add_f32_e32 v62, v62, v63
	v_add_f32_e32 v62, v64, v62
	v_pk_mul_f32 v[74:75], v[58:59], v[72:73]
	v_pk_mul_f32 v[58:59], v[58:59], v[58:59]
	v_add_f32_e32 v62, v65, v62
	v_add_f32_e32 v58, v58, v62
	v_pk_mul_f32 v[60:61], v[60:61], v[60:61]
	v_add_f32_e32 v58, v59, v58
	v_add_f32_e32 v58, v60, v58
	v_add_f32_e32 v58, v61, v58
	v_cvt_pk_bf16_f32 v72, v76, v77
	v_cvt_pk_bf16_f32 v73, v78, v79
	v_cvt_pk_bf16_f32 v74, v74, v75
	v_cvt_pk_bf16_f32 v75, v80, v81
	global_store_dwordx4 v[66:67], v[72:75], off
	s_branch .LBB0_1310

.LBB0_1310:
	v_mov_b32_e32 v60, v176
	v_mov_b32_e32 v61, v177
	v_mov_b32_e32 v62, v178
	v_mov_b32_e32 v63, v179
	s_nop 0
	v_mov_b32_e32 v70, v180
	v_mov_b32_e32 v71, v181
	v_mov_b32_e32 v72, v182
	v_mov_b32_e32 v73, v183
	v_mov_b32_e32 v246, 0x160000
	v_mov_b32_e32 v247, 0
	v_lshl_add_u64 v[228:229], v[226:227], 0, v[246:247]
	global_load_dwordx4 v[168:171], v[228:229], off nt
	global_load_dwordx4 v[172:175], v[228:229], off offset:16 nt
	global_load_dwordx4 v[176:179], v[228:229], off offset:512 nt
	global_load_dwordx4 v[180:183], v[228:229], off offset:528 nt
	s_and_b64 vcc, exec, s[92:93]
	v_pk_add_f32 v[56:57], v[56:57], v[62:63]
	v_pk_add_f32 v[54:55], v[54:55], v[60:61]
	v_pk_add_f32 v[52:53], v[52:53], v[72:73]
	v_pk_add_f32 v[50:51], v[50:51], v[70:71]
	global_store_dwordx4 v[68:69], v[54:57], off offset:512
	global_store_dwordx4 v[68:69], v[50:53], off offset:528
	s_cbranch_vccnz .LBB0_1314
	v_mov_b32_e32 v60, v242
	v_mov_b32_e32 v61, v243
	v_mov_b32_e32 v62, v244
	v_mov_b32_e32 v63, v245
	v_mov_b32_e32 v68, v238
	v_mov_b32_e32 v69, v239
	v_mov_b32_e32 v70, v240
	v_mov_b32_e32 v71, v241
	v_pk_mul_f32 v[68:69], v[54:55], v[68:69]
	v_mul_f32_e32 v55, v55, v55
	v_fmac_f32_e32 v55, v54, v54
	v_fmac_f32_e32 v55, v56, v56
	v_fmac_f32_e32 v55, v57, v57
	v_fmac_f32_e32 v55, v50, v50
	v_fmac_f32_e32 v55, v51, v51
	v_pk_mul_f32 v[64:65], v[56:57], v[70:71]
	v_pk_mul_f32 v[70:71], v[52:53], v[62:63]
	v_fmac_f32_e32 v55, v52, v52
	v_and_b32_e32 v52, 64, v200
	v_pk_mul_f32 v[62:63], v[50:51], v[60:61]
	v_xor_b32_e32 v51, 16, v200
	v_add_u32_e32 v52, 64, v52
	v_cmp_lt_i32_e32 vcc, v51, v52
	v_fmac_f32_e32 v55, v53, v53
	v_add_f32_e32 v50, v58, v55
	v_cndmask_b32_e32 v51, v200, v51, vcc
	v_lshlrev_b32_e32 v51, 2, v51
	ds_bpermute_b32 v51, v51, v50
	v_cvt_pk_bf16_f32 v60, v68, v69
	v_cvt_pk_bf16_f32 v61, v64, v65
	v_cvt_pk_bf16_f32 v62, v62, v63
	v_cvt_pk_bf16_f32 v63, v70, v71
	s_waitcnt lgkmcnt(0)
	v_add_f32_e32 v50, v50, v51
	v_xor_b32_e32 v51, 32, v200
	v_cmp_lt_i32_e32 vcc, v51, v52
	global_store_dwordx4 v[66:67], v[60:63], off offset:256
	s_nop 0
	v_cndmask_b32_e32 v51, v200, v51, vcc
	v_lshlrev_b32_e32 v51, 2, v51
	ds_bpermute_b32 v51, v51, v50
	s_and_saveexec_b64 s[22:23], s[90:91]
	s_cbranch_execz .LBB0_1313
	v_lshl_add_u64 v[52:53], v[140:141], 2, s[8:9]
	s_waitcnt lgkmcnt(0)
	v_add_f32_e32 v50, v50, v51
	global_atomic_add_f32 v[52:53], v50, off offset:512

.LBB0_1314:
	s_mov_b64 s[22:23], 0x48000
	s_waitcnt lgkmcnt(0)
	v_lshl_add_u64 v[50:51], v[144:145], 0, s[22:23]
	v_lshlrev_b64 v[52:53], 2, v[50:51]
	v_lshl_add_u64 v[54:55], s[0:1], 0, v[52:53]
	s_waitcnt vmcnt(16)
	v_mov_b32_e32 v56, v184
	v_mov_b32_e32 v57, v185
	v_mov_b32_e32 v58, v186
	v_mov_b32_e32 v59, v187
	v_mov_b32_e32 v60, v188
	v_mov_b32_e32 v61, v189
	v_mov_b32_e32 v62, v190
	v_mov_b32_e32 v63, v191
	s_and_b64 vcc, exec, s[92:93]
	v_lshl_add_u64 v[52:53], s[10:11], 0, v[52:53]
	v_lshl_add_u64 v[50:51], v[50:51], 1, s[6:7]
	v_pk_add_f32 v[48:49], v[48:49], v[58:59]
	v_pk_add_f32 v[46:47], v[46:47], v[56:57]
	v_pk_add_f32 v[44:45], v[44:45], v[62:63]
	v_pk_add_f32 v[42:43], v[42:43], v[60:61]
	global_store_dwordx4 v[52:53], v[46:49], off
	global_store_dwordx4 v[52:53], v[42:45], off offset:16
	s_cbranch_vccnz .LBB0_1316
	v_mov_b32_e32 v56, v234
	v_mov_b32_e32 v57, v235
	v_mov_b32_e32 v58, v236
	v_mov_b32_e32 v59, v237
	v_mov_b32_e32 v60, v230
	v_mov_b32_e32 v61, v231
	v_mov_b32_e32 v62, v232
	v_mov_b32_e32 v63, v233
	v_pk_mul_f32 v[64:65], v[44:45], v[58:59]
	v_pk_mul_f32 v[60:61], v[46:47], v[60:61]
	v_pk_mul_f32 v[46:47], v[46:47], v[46:47]
	v_pk_mul_f32 v[62:63], v[48:49], v[62:63]
	v_pk_mul_f32 v[48:49], v[48:49], v[48:49]
	v_add_f32_e32 v46, v46, v47
	v_add_f32_e32 v46, v48, v46
	v_pk_mul_f32 v[58:59], v[42:43], v[56:57]
	v_pk_mul_f32 v[42:43], v[42:43], v[42:43]
	v_add_f32_e32 v46, v49, v46
	v_add_f32_e32 v42, v42, v46
	v_pk_mul_f32 v[44:45], v[44:45], v[44:45]
	v_add_f32_e32 v42, v43, v42
	v_add_f32_e32 v42, v44, v42
	v_add_f32_e32 v42, v45, v42
	v_cvt_pk_bf16_f32 v56, v60, v61
	v_cvt_pk_bf16_f32 v57, v62, v63
	v_cvt_pk_bf16_f32 v58, v58, v59
	v_cvt_pk_bf16_f32 v59, v64, v65
	global_store_dwordx4 v[50:51], v[56:59], off
	s_branch .LBB0_1317

.LBB0_1317:
	v_mov_b32_e32 v44, v192
	v_mov_b32_e32 v45, v193
	v_mov_b32_e32 v46, v194
	v_mov_b32_e32 v47, v195
	s_nop 0
	v_mov_b32_e32 v54, v206
	v_mov_b32_e32 v55, v207
	v_mov_b32_e32 v56, v208
	v_mov_b32_e32 v57, v209
	s_and_b64 vcc, exec, s[92:93]
	v_pk_add_f32 v[40:41], v[40:41], v[46:47]
	v_pk_add_f32 v[38:39], v[38:39], v[44:45]
	v_pk_add_f32 v[36:37], v[36:37], v[56:57]
	v_pk_add_f32 v[34:35], v[34:35], v[54:55]
	global_store_dwordx4 v[52:53], v[38:41], off offset:512
	global_store_dwordx4 v[52:53], v[34:37], off offset:528
	s_cbranch_vccnz .LBB0_1321
	v_mov_b32_e32 v44, v242
	v_mov_b32_e32 v45, v243
	v_mov_b32_e32 v46, v244
	v_mov_b32_e32 v47, v245
	v_mov_b32_e32 v52, v238
	v_mov_b32_e32 v53, v239
	v_mov_b32_e32 v54, v240
	v_mov_b32_e32 v55, v241
	v_pk_mul_f32 v[52:53], v[38:39], v[52:53]
	v_mul_f32_e32 v39, v39, v39
	v_fmac_f32_e32 v39, v38, v38
	v_fmac_f32_e32 v39, v40, v40
	v_fmac_f32_e32 v39, v41, v41
	v_fmac_f32_e32 v39, v34, v34
	v_fmac_f32_e32 v39, v35, v35
	v_pk_mul_f32 v[48:49], v[40:41], v[54:55]
	v_pk_mul_f32 v[54:55], v[36:37], v[46:47]
	v_fmac_f32_e32 v39, v36, v36
	v_and_b32_e32 v36, 64, v200
	v_pk_mul_f32 v[46:47], v[34:35], v[44:45]
	v_xor_b32_e32 v35, 16, v200
	v_add_u32_e32 v36, 64, v36
	v_cmp_lt_i32_e32 vcc, v35, v36
	v_fmac_f32_e32 v39, v37, v37
	v_add_f32_e32 v34, v42, v39
	v_cndmask_b32_e32 v35, v200, v35, vcc
	v_lshlrev_b32_e32 v35, 2, v35
	ds_bpermute_b32 v35, v35, v34
	v_cvt_pk_bf16_f32 v44, v52, v53
	v_cvt_pk_bf16_f32 v45, v48, v49
	v_cvt_pk_bf16_f32 v46, v46, v47
	v_cvt_pk_bf16_f32 v47, v54, v55
	s_waitcnt lgkmcnt(0)
	v_add_f32_e32 v34, v34, v35
	v_xor_b32_e32 v35, 32, v200
	v_cmp_lt_i32_e32 vcc, v35, v36
	global_store_dwordx4 v[50:51], v[44:47], off offset:256
	s_nop 0
	v_cndmask_b32_e32 v35, v200, v35, vcc
	v_lshlrev_b32_e32 v35, 2, v35
	ds_bpermute_b32 v35, v35, v34
	s_and_saveexec_b64 s[22:23], s[90:91]
	s_cbranch_execz .LBB0_1320
	v_lshl_add_u64 v[36:37], v[140:141], 2, s[8:9]
	s_waitcnt lgkmcnt(0)
	v_add_f32_e32 v34, v34, v35
	global_atomic_add_f32 v[36:37], v34, off offset:576

.LBB0_1321:
	s_mov_b64 s[22:23], 0x50000
	s_waitcnt lgkmcnt(0)
	v_lshl_add_u64 v[34:35], v[144:145], 0, s[22:23]
	v_lshlrev_b64 v[36:37], 2, v[34:35]
	v_lshl_add_u64 v[38:39], s[0:1], 0, v[36:37]
	s_waitcnt vmcnt(12)
	v_mov_b32_e32 v40, v210
	v_mov_b32_e32 v41, v211
	v_mov_b32_e32 v42, v212
	v_mov_b32_e32 v43, v213
	v_mov_b32_e32 v44, v214
	v_mov_b32_e32 v45, v215
	v_mov_b32_e32 v46, v216
	v_mov_b32_e32 v47, v217
	s_and_b64 vcc, exec, s[92:93]
	v_lshl_add_u64 v[36:37], s[10:11], 0, v[36:37]
	v_lshl_add_u64 v[34:35], v[34:35], 1, s[6:7]
	v_pk_add_f32 v[32:33], v[32:33], v[42:43]
	v_pk_add_f32 v[30:31], v[30:31], v[40:41]
	v_pk_add_f32 v[28:29], v[28:29], v[46:47]
	v_pk_add_f32 v[26:27], v[26:27], v[44:45]
	global_store_dwordx4 v[36:37], v[30:33], off
	global_store_dwordx4 v[36:37], v[26:29], off offset:16
	s_cbranch_vccnz .LBB0_1323
	v_mov_b32_e32 v40, v234
	v_mov_b32_e32 v41, v235
	v_mov_b32_e32 v42, v236
	v_mov_b32_e32 v43, v237
	v_mov_b32_e32 v44, v230
	v_mov_b32_e32 v45, v231
	v_mov_b32_e32 v46, v232
	v_mov_b32_e32 v47, v233
	v_pk_mul_f32 v[48:49], v[28:29], v[42:43]
	v_pk_mul_f32 v[44:45], v[30:31], v[44:45]
	v_pk_mul_f32 v[30:31], v[30:31], v[30:31]
	v_pk_mul_f32 v[46:47], v[32:33], v[46:47]
	v_pk_mul_f32 v[32:33], v[32:33], v[32:33]
	v_add_f32_e32 v30, v30, v31
	v_add_f32_e32 v30, v32, v30
	v_pk_mul_f32 v[42:43], v[26:27], v[40:41]
	v_pk_mul_f32 v[26:27], v[26:27], v[26:27]
	v_add_f32_e32 v30, v33, v30
	v_add_f32_e32 v26, v26, v30
	v_pk_mul_f32 v[28:29], v[28:29], v[28:29]
	v_add_f32_e32 v26, v27, v26
	v_add_f32_e32 v26, v28, v26
	v_add_f32_e32 v26, v29, v26
	v_cvt_pk_bf16_f32 v40, v44, v45
	v_cvt_pk_bf16_f32 v41, v46, v47
	v_cvt_pk_bf16_f32 v42, v42, v43
	v_cvt_pk_bf16_f32 v43, v48, v49
	global_store_dwordx4 v[34:35], v[40:43], off
	s_branch .LBB0_1324

.LBB0_1324:
	v_mov_b32_e32 v28, v218
	v_mov_b32_e32 v29, v219
	v_mov_b32_e32 v30, v220
	v_mov_b32_e32 v31, v221
	s_nop 0
	v_mov_b32_e32 v38, v222
	v_mov_b32_e32 v39, v223
	v_mov_b32_e32 v40, v224
	v_mov_b32_e32 v41, v225
	s_and_b64 vcc, exec, s[92:93]
	v_pk_add_f32 v[24:25], v[24:25], v[30:31]
	v_pk_add_f32 v[22:23], v[22:23], v[28:29]
	v_pk_add_f32 v[20:21], v[20:21], v[40:41]
	v_pk_add_f32 v[18:19], v[18:19], v[38:39]
	global_store_dwordx4 v[36:37], v[22:25], off offset:512
	global_store_dwordx4 v[36:37], v[18:21], off offset:528
	s_cbranch_vccnz .LBB0_1328
	v_mov_b32_e32 v28, v242
	v_mov_b32_e32 v29, v243
	v_mov_b32_e32 v30, v244
	v_mov_b32_e32 v31, v245
	v_mov_b32_e32 v36, v238
	v_mov_b32_e32 v37, v239
	v_mov_b32_e32 v38, v240
	v_mov_b32_e32 v39, v241
	v_pk_mul_f32 v[36:37], v[22:23], v[36:37]
	v_mul_f32_e32 v23, v23, v23
	v_fmac_f32_e32 v23, v22, v22
	v_fmac_f32_e32 v23, v24, v24
	v_fmac_f32_e32 v23, v25, v25
	v_fmac_f32_e32 v23, v18, v18
	v_fmac_f32_e32 v23, v19, v19
	v_pk_mul_f32 v[32:33], v[24:25], v[38:39]
	v_pk_mul_f32 v[38:39], v[20:21], v[30:31]
	v_fmac_f32_e32 v23, v20, v20
	v_and_b32_e32 v20, 64, v200
	v_pk_mul_f32 v[30:31], v[18:19], v[28:29]
	v_xor_b32_e32 v19, 16, v200
	v_add_u32_e32 v20, 64, v20
	v_cmp_lt_i32_e32 vcc, v19, v20
	v_fmac_f32_e32 v23, v21, v21
	v_add_f32_e32 v18, v26, v23
	v_cndmask_b32_e32 v19, v200, v19, vcc
	v_lshlrev_b32_e32 v19, 2, v19
	ds_bpermute_b32 v19, v19, v18
	v_cvt_pk_bf16_f32 v28, v36, v37
	v_cvt_pk_bf16_f32 v29, v32, v33
	v_cvt_pk_bf16_f32 v30, v30, v31
	v_cvt_pk_bf16_f32 v31, v38, v39
	s_waitcnt lgkmcnt(0)
	v_add_f32_e32 v18, v18, v19
	v_xor_b32_e32 v19, 32, v200
	v_cmp_lt_i32_e32 vcc, v19, v20
	global_store_dwordx4 v[34:35], v[28:31], off offset:256
	s_nop 0
	v_cndmask_b32_e32 v19, v200, v19, vcc
	v_lshlrev_b32_e32 v19, 2, v19
	ds_bpermute_b32 v19, v19, v18
	s_and_saveexec_b64 s[22:23], s[90:91]
	s_cbranch_execz .LBB0_1327
	v_lshl_add_u64 v[20:21], v[140:141], 2, s[8:9]
	s_waitcnt lgkmcnt(0)
	v_add_f32_e32 v18, v18, v19
	global_atomic_add_f32 v[20:21], v18, off offset:640

.LBB0_1328:
	s_mov_b64 s[22:23], 0x58000
	s_waitcnt lgkmcnt(0)
	v_lshl_add_u64 v[18:19], v[144:145], 0, s[22:23]
	v_lshlrev_b64 v[20:21], 2, v[18:19]
	v_lshl_add_u64 v[22:23], s[0:1], 0, v[20:21]
	s_waitcnt vmcnt(8)
	v_mov_b32_e32 v24, v168
	v_mov_b32_e32 v25, v169
	v_mov_b32_e32 v26, v170
	v_mov_b32_e32 v27, v171
	v_mov_b32_e32 v28, v172
	v_mov_b32_e32 v29, v173
	v_mov_b32_e32 v30, v174
	v_mov_b32_e32 v31, v175
	s_and_b64 vcc, exec, s[92:93]
	v_lshl_add_u64 v[20:21], s[10:11], 0, v[20:21]
	v_lshl_add_u64 v[18:19], v[18:19], 1, s[6:7]
	v_pk_add_f32 v[16:17], v[16:17], v[26:27]
	v_pk_add_f32 v[14:15], v[14:15], v[24:25]
	v_pk_add_f32 v[12:13], v[12:13], v[30:31]
	v_pk_add_f32 v[10:11], v[10:11], v[28:29]
	global_store_dwordx4 v[20:21], v[14:17], off
	global_store_dwordx4 v[20:21], v[10:13], off offset:16
	s_cbranch_vccnz .LBB0_1330
	v_mov_b32_e32 v24, v234
	v_mov_b32_e32 v25, v235
	v_mov_b32_e32 v26, v236
	v_mov_b32_e32 v27, v237
	v_mov_b32_e32 v28, v230
	v_mov_b32_e32 v29, v231
	v_mov_b32_e32 v30, v232
	v_mov_b32_e32 v31, v233
	v_pk_mul_f32 v[32:33], v[12:13], v[26:27]
	v_pk_mul_f32 v[28:29], v[14:15], v[28:29]
	v_pk_mul_f32 v[14:15], v[14:15], v[14:15]
	v_pk_mul_f32 v[30:31], v[16:17], v[30:31]
	v_pk_mul_f32 v[16:17], v[16:17], v[16:17]
	v_add_f32_e32 v14, v14, v15
	v_add_f32_e32 v14, v16, v14
	v_pk_mul_f32 v[26:27], v[10:11], v[24:25]
	v_pk_mul_f32 v[10:11], v[10:11], v[10:11]
	v_add_f32_e32 v14, v17, v14
	v_add_f32_e32 v10, v10, v14
	v_pk_mul_f32 v[12:13], v[12:13], v[12:13]
	v_add_f32_e32 v10, v11, v10
	v_add_f32_e32 v10, v12, v10
	v_add_f32_e32 v10, v13, v10
	v_cvt_pk_bf16_f32 v24, v28, v29
	v_cvt_pk_bf16_f32 v25, v30, v31
	v_cvt_pk_bf16_f32 v26, v26, v27
	v_cvt_pk_bf16_f32 v27, v32, v33
	global_store_dwordx4 v[18:19], v[24:27], off
	s_branch .LBB0_1331

.LBB0_1331:
	v_mov_b32_e32 v12, v176
	v_mov_b32_e32 v13, v177
	v_mov_b32_e32 v14, v178
	v_mov_b32_e32 v15, v179
	s_nop 0
	v_mov_b32_e32 v22, v180
	v_mov_b32_e32 v23, v181
	v_mov_b32_e32 v24, v182
	v_mov_b32_e32 v25, v183
	s_and_b64 vcc, exec, s[92:93]
	v_pk_add_f32 v[8:9], v[8:9], v[14:15]
	v_pk_add_f32 v[6:7], v[6:7], v[12:13]
	v_pk_add_f32 v[4:5], v[4:5], v[24:25]
	v_pk_add_f32 v[2:3], v[2:3], v[22:23]
	global_store_dwordx4 v[20:21], v[6:9], off offset:512
	global_store_dwordx4 v[20:21], v[2:5], off offset:528
	s_cbranch_vccnz .LBB0_1335
	v_mov_b32_e32 v12, v242
	v_mov_b32_e32 v13, v243
	v_mov_b32_e32 v14, v244
	v_mov_b32_e32 v15, v245
	v_mov_b32_e32 v20, v238
	v_mov_b32_e32 v21, v239
	v_mov_b32_e32 v22, v240
	v_mov_b32_e32 v23, v241
	v_pk_mul_f32 v[20:21], v[6:7], v[20:21]
	v_mul_f32_e32 v7, v7, v7
	v_fmac_f32_e32 v7, v6, v6
	v_fmac_f32_e32 v7, v8, v8
	v_fmac_f32_e32 v7, v9, v9
	v_fmac_f32_e32 v7, v2, v2
	v_fmac_f32_e32 v7, v3, v3
	v_pk_mul_f32 v[16:17], v[8:9], v[22:23]
	v_pk_mul_f32 v[22:23], v[4:5], v[14:15]
	v_fmac_f32_e32 v7, v4, v4
	v_and_b32_e32 v4, 64, v200
	v_pk_mul_f32 v[14:15], v[2:3], v[12:13]
	v_xor_b32_e32 v3, 16, v200
	v_add_u32_e32 v4, 64, v4
	v_cmp_lt_i32_e32 vcc, v3, v4
	v_fmac_f32_e32 v7, v5, v5
	v_add_f32_e32 v2, v10, v7
	v_cndmask_b32_e32 v3, v200, v3, vcc
	v_lshlrev_b32_e32 v3, 2, v3
	ds_bpermute_b32 v3, v3, v2
	v_cvt_pk_bf16_f32 v12, v20, v21
	v_cvt_pk_bf16_f32 v13, v16, v17
	v_cvt_pk_bf16_f32 v14, v14, v15
	v_cvt_pk_bf16_f32 v15, v22, v23
	s_waitcnt lgkmcnt(0)
	v_add_f32_e32 v2, v2, v3
	v_xor_b32_e32 v3, 32, v200
	v_cmp_lt_i32_e32 vcc, v3, v4
	global_store_dwordx4 v[18:19], v[12:15], off offset:256
	s_nop 0
	v_cndmask_b32_e32 v3, v200, v3, vcc
	v_lshlrev_b32_e32 v3, 2, v3
	ds_bpermute_b32 v3, v3, v2
	s_and_saveexec_b64 s[22:23], s[90:91]
	s_cbranch_execz .LBB0_1334
	v_lshl_add_u64 v[4:5], v[140:141], 2, s[8:9]
	s_waitcnt lgkmcnt(0)
	v_add_f32_e32 v2, v2, v3
	global_atomic_add_f32 v[4:5], v2, off offset:704
